# in-proj GEMM tile order: the 128 tiles of the padded 17th column block moved to the last round, and the MFMAs of their all-padding column half (bj=1) skipped; the other 2048 tiles enumerate as a 16-co
# speedup vs baseline: 1.0396x; 1.0067x over previous
.LBB0_331:
	s_mov_b32 s29, s70
	s_lshr_b32 s30, s28, 6
	s_cmpk_eq_u32 s28, 0x1100
	s_cselect_b32 s30, 64, s30
	s_lshr_b32 s18, s28, 1
	s_waitcnt vmcnt(0)
	v_mov_b32_e32 v14, v160
	s_cmp_lt_i32 s29, s18
	s_cselect_b64 s[8:9], -1, 0
	s_cmp_ge_i32 s29, s18
	v_readfirstlane_b32 s31, v14
	s_cbranch_scc1 .LBB0_333
	v_cvt_f32_u32_e32 v0, s30
	s_ashr_i32 s11, s29, 31
	s_lshr_b32 s11, s11, 29
	s_add_i32 s11, s29, s11
	v_rcp_iflag_f32_e32 v0, v0
	s_ashr_i32 s19, s11, 3
	s_and_b32 s11, s11, -8
	s_sub_i32 s11, s29, s11
	v_mul_f32_e32 v0, 0x4f7ffffe, v0
	v_cvt_u32_f32_e32 v0, v0
	s_lshl_b32 s2, s30, 2
	s_lshr_b32 s20, s11, 31
	s_or_b32 s2, s2, s20
	s_sub_i32 s20, 0, s30
	v_readfirstlane_b32 s21, v0
	s_mul_i32 s2, s11, s2
	s_mul_i32 s20, s20, s21
	s_add_i32 s2, s2, s19
	s_mul_hi_u32 s20, s21, s20
	s_abs_i32 s19, s2
	s_add_i32 s21, s21, s20
	s_mul_hi_u32 s20, s19, s21
	s_mul_i32 s21, s20, s30
	s_sub_i32 s19, s19, s21
	s_ashr_i32 s11, s2, 31
	s_add_i32 s21, s20, 1
	s_sub_i32 s22, s19, s30
	s_cmp_ge_u32 s19, s30
	s_cselect_b32 s20, s21, s20
	s_cselect_b32 s19, s22, s19
	s_add_i32 s21, s20, 1
	s_cmp_ge_u32 s19, s30
	s_cselect_b32 s19, s21, s20
	s_xor_b32 s19, s19, s11
	s_sub_i32 s11, s19, s11
	s_lshl_b32 s19, s11, 2
	s_sub_i32 s20, 0x80, s19
	s_min_i32 s22, s20, 4
	s_sext_i32_i16 s20, s22
	v_cvt_f32_i32_e32 v0, s20
	s_mul_i32 s11, s11, s30
	s_sub_i32 s2, s2, s11
	s_sext_i32_i16 s11, s2
	v_cvt_f32_i32_e32 v2, s11
	v_rcp_iflag_f32_e32 v3, v0
	s_xor_b32 s11, s11, s20
	s_ashr_i32 s11, s11, 30
	s_or_b32 s11, s11, 1
	v_mul_f32_e32 v3, v2, v3
	v_trunc_f32_e32 v3, v3
	v_fma_f32 v2, -v3, v0, v2
	v_cvt_i32_f32_e32 v3, v3
	v_cmp_ge_f32_e64 s[20:21], |v2|, |v0|
	s_and_b64 s[20:21], s[20:21], exec
	s_cselect_b32 s11, s11, 0
	v_readfirstlane_b32 s20, v3
	s_add_i32 s11, s20, s11
	s_sext_i32_i16 s53, s11
	s_mul_i32 s11, s11, s22
	s_sub_i32 s2, s2, s11
	s_sext_i32_i16 s2, s2
	s_add_i32 s54, s19, s2

.LBB0_336:
	s_add_u32 s20, s12, s6
	s_addc_u32 s21, s13, s7
	s_add_i32 m0, s35, 0x18000
	v_lshl_add_u64 v[12:13], v[12:13], 0, s[88:89]
	s_waitcnt vmcnt(4)
	s_barrier
	global_load_lds_dwordx4 v[12:13], off
	v_lshl_add_u64 v[10:11], v[10:11], 0, s[88:89]
	s_add_i32 m0, s35, 0x1a000
	s_add_i32 s39, s35, 0x8000
	global_load_lds_dwordx4 v[10:11], off
	v_lshl_add_u64 v[8:9], v[8:9], 0, s[88:89]
	s_mov_b32 m0, s39
	s_add_i32 s40, s35, 0xa000
	global_load_lds_dwordx4 v[8:9], off
	v_lshl_add_u64 v[6:7], v[6:7], 0, s[88:89]
	s_mov_b32 m0, s40
	v_lshl_add_u64 v[4:5], v[4:5], 0, s[88:89]
	global_load_lds_dwordx4 v[6:7], off
	s_add_i32 m0, s35, 0x1c000
	v_lshl_add_u64 v[2:3], v[2:3], 0, s[88:89]
	global_load_lds_dwordx4 v[4:5], off
	s_add_i32 m0, s35, 0x1e000
	s_lshl_b32 s6, s9, 13
	global_load_lds_dwordx4 v[2:3], off
	v_lshrrev_b32_e32 v3, 1, v14
	v_and_b32_e32 v3, 24, v3
	v_and_b32_e32 v2, 15, v14
	v_lshlrev_b32_e32 v4, 1, v3
	v_lshl_or_b32 v145, s9, 6, v2
	v_lshl_or_b32 v2, v2, 6, v4
	v_lshlrev_b32_e32 v4, 2, v14
	v_and_b32_e32 v4, 32, v4
	v_bitop3_b32 v5, v2, s6, v4 bitop3:0xde
	s_lshl_b32 s6, s8, 5
	s_and_b32 s6, s6, 0x60
	s_lshl_b32 s7, s6, 7
	v_bitop3_b32 v175, v2, s7, v4 bitop3:0xde
	v_cvt_f32_ubyte0_e32 v2, s30
	v_rcp_iflag_f32_e32 v2, v2
	v_or_b32_e32 v176, s6, v3
	s_sub_i32 s6, 0, s30
	v_mov_b32_e32 v3, v1
	v_mul_f32_e32 v2, 0x4f7ffffe, v2
	v_cvt_u32_f32_e32 v2, v2
	s_waitcnt vmcnt(6)
	s_lshr_b32 s41, s10, 6
	s_add_i32 s42, s41, -2
	v_readfirstlane_b32 s7, v2
	v_add_u32_e32 v2, v17, v15
	v_add_lshl_u32 v2, v2, v16, 1
	s_mul_i32 s6, s6, s7
	v_lshl_add_u64 v[152:153], s[62:63], 0, v[2:3]
	v_add_u32_e32 v2, v20, v18
	s_mul_hi_u32 s6, s7, s6
	v_add_lshl_u32 v2, v2, v19, 1
	s_ashr_i32 s43, s29, 31
	s_mov_b32 s19, s63
	s_lshl_b32 s44, s30, 2
	s_mov_b32 s45, 0
	s_add_i32 s46, s7, s6
	v_lshl_add_u64 v[154:155], s[62:63], 0, v[2:3]
	v_add_u32_e32 v177, 0, v5
	s_barrier
	s_branch .LBB0_338

.LBB0_338:
	s_add_i32 s45, s45, 1
	s_mul_i32 s6, s45, s3
	s_mul_hi_u32 s7, s45, s50
	s_add_i32 s7, s7, s6
	s_mul_i32 s6, s45, s50
	s_add_u32 s10, s6, s29
	s_addc_u32 s11, s7, s43
	v_mov_b64_e32 v[2:3], s[18:19]
	v_cmp_ge_i64_e64 s[6:7], s[10:11], v[2:3]
	v_cmp_lt_i64_e64 s[8:9], s[10:11], v[2:3]
	s_and_b64 vcc, exec, s[6:7]
	s_cbranch_vccnz .LBB0_340
	s_cmpk_lt_u32 s10, 0x800
	s_cbranch_scc1 .Lgm_norm
	s_mov_b32 s47, 16
	s_sub_i32 s52, s10, 0x800
	s_branch .LBB0_340
.Lgm_norm:
	s_ashr_i32 s11, s10, 31
	s_lshr_b32 s11, s11, 29
	s_add_i32 s11, s10, s11
	s_ashr_i32 s26, s11, 3
	s_and_b32 s11, s11, -8
	s_sub_i32 s10, s10, s11
	s_lshr_b32 s11, s10, 31
	s_or_b32 s11, s44, s11
	s_mul_i32 s10, s11, s10
	s_add_i32 s10, s10, s26
	s_abs_i32 s26, s10
	s_mul_hi_u32 s27, s26, s46
	s_mul_i32 s47, s27, s30
	s_sub_i32 s26, s26, s47
	s_ashr_i32 s11, s10, 31
	s_add_i32 s47, s27, 1
	s_sub_i32 s52, s26, s30
	s_cmp_ge_u32 s26, s30
	s_cselect_b32 s27, s47, s27
	s_cselect_b32 s26, s52, s26
	s_add_i32 s47, s27, 1
	s_cmp_ge_u32 s26, s30
	s_cselect_b32 s26, s47, s27
	s_xor_b32 s26, s26, s11
	s_sub_i32 s11, s26, s11
	s_lshl_b32 s26, s11, 2
	s_sub_i32 s27, 0x80, s26
	s_min_i32 s27, s27, 4
	s_abs_i32 s47, s27
	v_cvt_f32_u32_e32 v2, s47
	s_sub_i32 s55, 0, s47
	s_mul_i32 s11, s11, s30
	s_sub_i32 s10, s10, s11
	v_rcp_iflag_f32_e32 v2, v2
	s_abs_i32 s52, s10
	s_xor_b32 s11, s10, s27
	s_ashr_i32 s11, s11, 31
	v_mul_f32_e32 v2, 0x4f7ffffe, v2
	v_cvt_u32_f32_e32 v2, v2
	s_nop 0
	v_readfirstlane_b32 s59, v2
	s_mul_i32 s55, s55, s59
	s_mul_hi_u32 s55, s59, s55
	s_add_i32 s59, s59, s55
	s_mul_hi_u32 s55, s52, s59
	s_mul_i32 s59, s55, s47
	s_sub_i32 s52, s52, s59
	s_add_i32 s59, s55, 1
	s_sub_i32 s60, s52, s47
	s_cmp_ge_u32 s52, s47
	s_cselect_b32 s55, s59, s55
	s_cselect_b32 s52, s60, s52
	s_add_i32 s59, s55, 1
	s_cmp_ge_u32 s52, s47
	s_cselect_b32 s47, s59, s55
	s_xor_b32 s47, s47, s11
	s_sub_i32 s47, s47, s11
	s_mul_i32 s11, s47, s27
	s_sub_i32 s10, s10, s11
	s_add_i32 s52, s10, s26

.LBB0_345:
	s_add_i32 s60, s24, 2
	s_add_u32 s26, s22, 0x80
	s_addc_u32 s25, s23, 0
	s_add_i32 s61, 0, 0x10000
	v_add_u32_e32 v178, s61, v175
	ds_read_b128 v[130:133], v178
	ds_read_b128 v[134:137], v178 offset:1024
	ds_read_b128 v[156:159], v178 offset:2048
	ds_read_b128 v[178:181], v178 offset:3072
	s_cmp_eq_u32 s42, s24
	s_cselect_b32 s24, s8, s26
	s_cselect_b32 s25, s9, s25
	s_cselect_b32 s27, s11, s59
	s_cselect_b32 s26, s10, s55
	v_lshl_add_u64 v[202:203], s[22:23], 0, v[152:153]
	s_add_i32 m0, s35, 0xc000
	ds_read_b128 v[182:185], v177
	ds_read_b128 v[186:189], v177 offset:1024
	ds_read_b128 v[190:193], v177 offset:2048
	ds_read_b128 v[194:197], v177 offset:3072
	ds_read_b128 v[198:201], v177 offset:4096
	ds_read_b128 v[206:209], v177 offset:5120
	ds_read_b128 v[210:213], v177 offset:6144
	ds_read_b128 v[214:217], v177 offset:7168
	global_load_lds_dwordx4 v[202:203], off
	v_lshl_add_u64 v[202:203], s[22:23], 0, v[154:155]
	s_add_i32 m0, s35, 0xe000
	s_nop 0
	global_load_lds_dwordx4 v[202:203], off
	s_waitcnt lgkmcnt(8)
	s_barrier
	s_waitcnt lgkmcnt(0)
	s_setprio 1
	s_waitcnt lgkmcnt(0)
	v_mfma_f32_16x16x32_bf16 v[126:129], v[130:133], v[182:185], v[126:129]
	v_mfma_f32_16x16x32_bf16 v[122:125], v[156:159], v[182:185], v[122:125]
	v_mfma_f32_16x16x32_bf16 v[110:113], v[130:133], v[190:193], v[110:113]
	v_mfma_f32_16x16x32_bf16 v[106:109], v[156:159], v[190:193], v[106:109]
	v_mfma_f32_16x16x32_bf16 v[94:97], v[130:133], v[198:201], v[94:97]
	v_mfma_f32_16x16x32_bf16 v[90:93], v[156:159], v[198:201], v[90:93]
	v_mfma_f32_16x16x32_bf16 v[78:81], v[130:133], v[210:213], v[78:81]
	v_mfma_f32_16x16x32_bf16 v[74:77], v[156:159], v[210:213], v[74:77]
	v_mfma_f32_16x16x32_bf16 v[126:129], v[134:137], v[186:189], v[126:129]
	v_mfma_f32_16x16x32_bf16 v[122:125], v[178:181], v[186:189], v[122:125]
	v_mfma_f32_16x16x32_bf16 v[110:113], v[134:137], v[194:197], v[110:113]
	v_mfma_f32_16x16x32_bf16 v[106:109], v[178:181], v[194:197], v[106:109]
	v_mfma_f32_16x16x32_bf16 v[94:97], v[134:137], v[206:209], v[94:97]
	v_mfma_f32_16x16x32_bf16 v[90:93], v[178:181], v[206:209], v[90:93]
	v_mfma_f32_16x16x32_bf16 v[78:81], v[134:137], v[214:217], v[78:81]
	v_mfma_f32_16x16x32_bf16 v[74:77], v[178:181], v[214:217], v[74:77]
	s_setprio 0
	s_barrier
	s_add_i32 s64, 0, 0x14000
	v_add_u32_e32 v202, s64, v175
	s_add_i32 s61, s61, s34
	ds_read_b128 v[218:221], v202
	ds_read_b128 v[222:225], v202 offset:1024
	ds_read_b128 v[226:229], v202 offset:2048
	ds_read_b128 v[230:233], v202 offset:3072
	v_lshl_add_u64 v[202:203], s[26:27], 0, v[0:1]
	s_mov_b32 m0, s61
	v_lshl_add_u64 v[234:235], s[26:27], 0, v[150:151]
	global_load_lds_dwordx4 v[202:203], off
	s_add_i32 m0, s61, 0x2000
	s_nop 0
	global_load_lds_dwordx4 v[234:235], off
	s_barrier
	s_waitcnt lgkmcnt(0)
	s_setprio 1
	s_waitcnt lgkmcnt(0)
	s_cmp_eq_u32 s53, 16
	s_cbranch_scc1 .Lgm_skip1
	v_mfma_f32_16x16x32_bf16 v[118:121], v[218:221], v[182:185], v[118:121]
	v_mfma_f32_16x16x32_bf16 v[114:117], v[226:229], v[182:185], v[114:117]
	v_mfma_f32_16x16x32_bf16 v[102:105], v[218:221], v[190:193], v[102:105]
	v_mfma_f32_16x16x32_bf16 v[98:101], v[226:229], v[190:193], v[98:101]
	v_mfma_f32_16x16x32_bf16 v[86:89], v[218:221], v[198:201], v[86:89]
	v_mfma_f32_16x16x32_bf16 v[82:85], v[226:229], v[198:201], v[82:85]
	v_mfma_f32_16x16x32_bf16 v[70:73], v[218:221], v[210:213], v[70:73]
	v_mfma_f32_16x16x32_bf16 v[66:69], v[226:229], v[210:213], v[66:69]
	v_mfma_f32_16x16x32_bf16 v[118:121], v[222:225], v[186:189], v[118:121]
	v_mfma_f32_16x16x32_bf16 v[114:117], v[230:233], v[186:189], v[114:117]
	v_mfma_f32_16x16x32_bf16 v[102:105], v[222:225], v[194:197], v[102:105]
	v_mfma_f32_16x16x32_bf16 v[98:101], v[230:233], v[194:197], v[98:101]
	v_mfma_f32_16x16x32_bf16 v[86:89], v[222:225], v[206:209], v[86:89]
	v_mfma_f32_16x16x32_bf16 v[82:85], v[230:233], v[206:209], v[82:85]
	v_mfma_f32_16x16x32_bf16 v[70:73], v[222:225], v[214:217], v[70:73]
	v_mfma_f32_16x16x32_bf16 v[66:69], v[230:233], v[214:217], v[66:69]
.Lgm_skip1:
	s_setprio 0
	s_mov_b32 m0, s35
	v_lshl_add_u64 v[236:237], s[24:25], 0, v[146:147]
	s_barrier
	ds_read_b128 v[182:185], v177 offset:16384
	ds_read_b128 v[186:189], v177 offset:17408
	ds_read_b128 v[190:193], v177 offset:18432
	ds_read_b128 v[194:197], v177 offset:19456
	ds_read_b128 v[198:201], v177 offset:20480
	ds_read_b128 v[206:209], v177 offset:21504
	ds_read_b128 v[210:213], v177 offset:22528
	ds_read_b128 v[214:217], v177 offset:23552
	global_load_lds_dwordx4 v[236:237], off
	v_lshl_add_u64 v[238:239], s[24:25], 0, v[148:149]
	s_mov_b32 m0, s36
	s_nop 0
	global_load_lds_dwordx4 v[238:239], off
	s_barrier
	s_waitcnt lgkmcnt(0)
	s_setprio 1
	s_waitcnt lgkmcnt(0)
	v_mfma_f32_16x16x32_bf16 v[62:65], v[130:133], v[182:185], v[62:65]
	v_mfma_f32_16x16x32_bf16 v[58:61], v[156:159], v[182:185], v[58:61]
	v_mfma_f32_16x16x32_bf16 v[46:49], v[130:133], v[190:193], v[46:49]
	v_mfma_f32_16x16x32_bf16 v[42:45], v[156:159], v[190:193], v[42:45]
	v_mfma_f32_16x16x32_bf16 v[30:33], v[130:133], v[198:201], v[30:33]
	v_mfma_f32_16x16x32_bf16 v[26:29], v[156:159], v[198:201], v[26:29]
	v_mfma_f32_16x16x32_bf16 v[14:17], v[130:133], v[210:213], v[14:17]
	v_mfma_f32_16x16x32_bf16 v[10:13], v[156:159], v[210:213], v[10:13]
	v_mfma_f32_16x16x32_bf16 v[62:65], v[134:137], v[186:189], v[62:65]
	v_mfma_f32_16x16x32_bf16 v[58:61], v[178:181], v[186:189], v[58:61]
	v_mfma_f32_16x16x32_bf16 v[46:49], v[134:137], v[194:197], v[46:49]
	v_mfma_f32_16x16x32_bf16 v[42:45], v[178:181], v[194:197], v[42:45]
	v_mfma_f32_16x16x32_bf16 v[30:33], v[134:137], v[206:209], v[30:33]
	v_mfma_f32_16x16x32_bf16 v[26:29], v[178:181], v[206:209], v[26:29]
	v_mfma_f32_16x16x32_bf16 v[14:17], v[134:137], v[214:217], v[14:17]
	v_mfma_f32_16x16x32_bf16 v[10:13], v[178:181], v[214:217], v[10:13]
	s_setprio 0
	s_barrier
	s_add_u32 s26, s26, s62
	s_addc_u32 s27, s27, 0
	s_add_i32 s61, s64, s34
	v_lshl_add_u64 v[240:241], s[26:27], 0, v[0:1]
	s_mov_b32 m0, s61
	v_lshl_add_u64 v[242:243], s[26:27], 0, v[150:151]
	global_load_lds_dwordx4 v[240:241], off
	s_add_i32 m0, s61, 0x2000
	s_nop 0
	global_load_lds_dwordx4 v[242:243], off
	s_waitcnt vmcnt(6)
	s_barrier
	s_setprio 1
	s_cmp_eq_u32 s53, 16
	s_cbranch_scc1 .Lgm_skip2
	v_mfma_f32_16x16x32_bf16 v[54:57], v[218:221], v[182:185], v[54:57]
	v_mfma_f32_16x16x32_bf16 v[50:53], v[226:229], v[182:185], v[50:53]
	v_mfma_f32_16x16x32_bf16 v[38:41], v[218:221], v[190:193], v[38:41]
	v_mfma_f32_16x16x32_bf16 v[34:37], v[226:229], v[190:193], v[34:37]
	v_mfma_f32_16x16x32_bf16 v[22:25], v[218:221], v[198:201], v[22:25]
	v_mfma_f32_16x16x32_bf16 v[18:21], v[226:229], v[198:201], v[18:21]
	v_mfma_f32_16x16x32_bf16 v[6:9], v[218:221], v[210:213], v[6:9]
	v_mfma_f32_16x16x32_bf16 v[2:5], v[226:229], v[210:213], v[2:5]
	v_mfma_f32_16x16x32_bf16 v[54:57], v[222:225], v[186:189], v[54:57]
	v_mfma_f32_16x16x32_bf16 v[50:53], v[230:233], v[186:189], v[50:53]
	v_mfma_f32_16x16x32_bf16 v[38:41], v[222:225], v[194:197], v[38:41]
	v_mfma_f32_16x16x32_bf16 v[34:37], v[230:233], v[194:197], v[34:37]
	v_mfma_f32_16x16x32_bf16 v[22:25], v[222:225], v[206:209], v[22:25]
	v_mfma_f32_16x16x32_bf16 v[18:21], v[230:233], v[206:209], v[18:21]
	v_mfma_f32_16x16x32_bf16 v[6:9], v[222:225], v[214:217], v[6:9]
	v_mfma_f32_16x16x32_bf16 v[2:5], v[230:233], v[214:217], v[2:5]
.Lgm_skip2:
	s_setprio 0
	s_add_i32 s26, 0, 0x18000
	v_add_u32_e32 v178, s26, v175
	s_barrier
	ds_read_b128 v[130:133], v178
	ds_read_b128 v[134:137], v178 offset:1024
	ds_read_b128 v[156:159], v178 offset:2048
	ds_read_b128 v[178:181], v178 offset:3072
	s_add_u32 s24, s24, s62
	s_addc_u32 s25, s25, 0
	s_mov_b32 m0, s37
	v_lshl_add_u64 v[218:219], s[24:25], 0, v[146:147]
	ds_read_b128 v[182:185], v177 offset:32768
	ds_read_b128 v[186:189], v177 offset:33792
	ds_read_b128 v[190:193], v177 offset:34816
	ds_read_b128 v[194:197], v177 offset:35840
	ds_read_b128 v[198:201], v177 offset:36864
	ds_read_b128 v[206:209], v177 offset:37888
	ds_read_b128 v[210:213], v177 offset:38912
	ds_read_b128 v[214:217], v177 offset:39936
	global_load_lds_dwordx4 v[218:219], off
	v_lshl_add_u64 v[218:219], s[24:25], 0, v[148:149]
	s_mov_b32 m0, s38
	s_nop 0
	global_load_lds_dwordx4 v[218:219], off
	s_waitcnt lgkmcnt(8)
	s_barrier
	s_waitcnt lgkmcnt(0)
	s_setprio 1
	s_waitcnt lgkmcnt(0)
	v_mfma_f32_16x16x32_bf16 v[126:129], v[130:133], v[182:185], v[126:129]
	v_mfma_f32_16x16x32_bf16 v[122:125], v[156:159], v[182:185], v[122:125]
	v_mfma_f32_16x16x32_bf16 v[110:113], v[130:133], v[190:193], v[110:113]
	v_mfma_f32_16x16x32_bf16 v[106:109], v[156:159], v[190:193], v[106:109]
	v_mfma_f32_16x16x32_bf16 v[94:97], v[130:133], v[198:201], v[94:97]
	v_mfma_f32_16x16x32_bf16 v[90:93], v[156:159], v[198:201], v[90:93]
	v_mfma_f32_16x16x32_bf16 v[78:81], v[130:133], v[210:213], v[78:81]
	v_mfma_f32_16x16x32_bf16 v[74:77], v[156:159], v[210:213], v[74:77]
	v_mfma_f32_16x16x32_bf16 v[126:129], v[134:137], v[186:189], v[126:129]
	v_mfma_f32_16x16x32_bf16 v[122:125], v[178:181], v[186:189], v[122:125]
	v_mfma_f32_16x16x32_bf16 v[110:113], v[134:137], v[194:197], v[110:113]
	v_mfma_f32_16x16x32_bf16 v[106:109], v[178:181], v[194:197], v[106:109]
	v_mfma_f32_16x16x32_bf16 v[94:97], v[134:137], v[206:209], v[94:97]
	v_mfma_f32_16x16x32_bf16 v[90:93], v[178:181], v[206:209], v[90:93]
	v_mfma_f32_16x16x32_bf16 v[78:81], v[134:137], v[214:217], v[78:81]
	v_mfma_f32_16x16x32_bf16 v[74:77], v[178:181], v[214:217], v[74:77]
	s_setprio 0
	s_barrier
	s_add_i32 s24, 0, 0x1c000
	s_add_i32 s25, s26, s34
	v_add_u32_e32 v230, s24, v175
	v_lshl_add_u64 v[202:203], v[202:203], 0, s[88:89]
	s_mov_b32 m0, s25
	ds_read_b128 v[218:221], v230
	ds_read_b128 v[222:225], v230 offset:1024
	ds_read_b128 v[226:229], v230 offset:2048
	ds_read_b128 v[230:233], v230 offset:3072
	global_load_lds_dwordx4 v[202:203], off
	v_lshl_add_u64 v[202:203], v[234:235], 0, s[88:89]
	s_add_i32 m0, s25, 0x2000
	s_nop 0
	global_load_lds_dwordx4 v[202:203], off
	s_barrier
	s_waitcnt lgkmcnt(0)
	s_setprio 1
	s_waitcnt lgkmcnt(0)
	s_cmp_eq_u32 s53, 16
	s_cbranch_scc1 .Lgm_skip3
	v_mfma_f32_16x16x32_bf16 v[118:121], v[218:221], v[182:185], v[118:121]
	v_mfma_f32_16x16x32_bf16 v[114:117], v[226:229], v[182:185], v[114:117]
	v_mfma_f32_16x16x32_bf16 v[102:105], v[218:221], v[190:193], v[102:105]
	v_mfma_f32_16x16x32_bf16 v[98:101], v[226:229], v[190:193], v[98:101]
	v_mfma_f32_16x16x32_bf16 v[86:89], v[218:221], v[198:201], v[86:89]
	v_mfma_f32_16x16x32_bf16 v[82:85], v[226:229], v[198:201], v[82:85]
	v_mfma_f32_16x16x32_bf16 v[70:73], v[218:221], v[210:213], v[70:73]
	v_mfma_f32_16x16x32_bf16 v[66:69], v[226:229], v[210:213], v[66:69]
	v_mfma_f32_16x16x32_bf16 v[118:121], v[222:225], v[186:189], v[118:121]
	v_mfma_f32_16x16x32_bf16 v[114:117], v[230:233], v[186:189], v[114:117]
	v_mfma_f32_16x16x32_bf16 v[102:105], v[222:225], v[194:197], v[102:105]
	v_mfma_f32_16x16x32_bf16 v[98:101], v[230:233], v[194:197], v[98:101]
	v_mfma_f32_16x16x32_bf16 v[86:89], v[222:225], v[206:209], v[86:89]
	v_mfma_f32_16x16x32_bf16 v[82:85], v[230:233], v[206:209], v[82:85]
	v_mfma_f32_16x16x32_bf16 v[70:73], v[222:225], v[214:217], v[70:73]
	v_mfma_f32_16x16x32_bf16 v[66:69], v[230:233], v[214:217], v[66:69]
.Lgm_skip3:
	s_setprio 0
	s_mov_b32 m0, s39
	v_lshl_add_u64 v[202:203], v[236:237], 0, s[88:89]
	s_barrier
	ds_read_b128 v[182:185], v177 offset:49152
	ds_read_b128 v[186:189], v177 offset:50176
	ds_read_b128 v[190:193], v177 offset:51200
	ds_read_b128 v[194:197], v177 offset:52224
	ds_read_b128 v[198:201], v177 offset:53248
	ds_read_b128 v[206:209], v177 offset:54272
	ds_read_b128 v[210:213], v177 offset:55296
	ds_read_b128 v[214:217], v177 offset:56320
	global_load_lds_dwordx4 v[202:203], off
	v_lshl_add_u64 v[202:203], v[238:239], 0, s[88:89]
	s_mov_b32 m0, s40
	s_nop 0
	global_load_lds_dwordx4 v[202:203], off
	s_barrier
	s_waitcnt lgkmcnt(0)
	s_setprio 1
	s_waitcnt lgkmcnt(0)
	v_mfma_f32_16x16x32_bf16 v[62:65], v[130:133], v[182:185], v[62:65]
	v_mfma_f32_16x16x32_bf16 v[58:61], v[156:159], v[182:185], v[58:61]
	v_mfma_f32_16x16x32_bf16 v[46:49], v[130:133], v[190:193], v[46:49]
	v_mfma_f32_16x16x32_bf16 v[42:45], v[156:159], v[190:193], v[42:45]
	v_mfma_f32_16x16x32_bf16 v[30:33], v[130:133], v[198:201], v[30:33]
	v_mfma_f32_16x16x32_bf16 v[26:29], v[156:159], v[198:201], v[26:29]
	v_mfma_f32_16x16x32_bf16 v[14:17], v[130:133], v[210:213], v[14:17]
	v_mfma_f32_16x16x32_bf16 v[10:13], v[156:159], v[210:213], v[10:13]
	v_mfma_f32_16x16x32_bf16 v[62:65], v[134:137], v[186:189], v[62:65]
	v_mfma_f32_16x16x32_bf16 v[58:61], v[178:181], v[186:189], v[58:61]
	v_mfma_f32_16x16x32_bf16 v[46:49], v[134:137], v[194:197], v[46:49]
	v_mfma_f32_16x16x32_bf16 v[42:45], v[178:181], v[194:197], v[42:45]
	v_mfma_f32_16x16x32_bf16 v[30:33], v[134:137], v[206:209], v[30:33]
	v_mfma_f32_16x16x32_bf16 v[26:29], v[178:181], v[206:209], v[26:29]
	v_mfma_f32_16x16x32_bf16 v[14:17], v[134:137], v[214:217], v[14:17]
	v_mfma_f32_16x16x32_bf16 v[10:13], v[178:181], v[214:217], v[10:13]
	s_setprio 0
	s_barrier
	s_add_i32 s24, s24, s34
	v_lshl_add_u64 v[130:131], v[240:241], 0, s[88:89]
	s_mov_b32 m0, s24
	s_nop 0
	global_load_lds_dwordx4 v[130:131], off
	v_lshl_add_u64 v[130:131], v[242:243], 0, s[88:89]
	s_add_i32 m0, s24, 0x2000
	s_nop 0
	global_load_lds_dwordx4 v[130:131], off
	s_waitcnt vmcnt(6)
	s_barrier
	s_setprio 1
	s_cmp_eq_u32 s53, 16
	s_cbranch_scc1 .Lgm_skip4
	v_mfma_f32_16x16x32_bf16 v[54:57], v[218:221], v[182:185], v[54:57]
	v_mfma_f32_16x16x32_bf16 v[50:53], v[226:229], v[182:185], v[50:53]
	v_mfma_f32_16x16x32_bf16 v[38:41], v[218:221], v[190:193], v[38:41]
	v_mfma_f32_16x16x32_bf16 v[34:37], v[226:229], v[190:193], v[34:37]
	v_mfma_f32_16x16x32_bf16 v[22:25], v[218:221], v[198:201], v[22:25]
	v_mfma_f32_16x16x32_bf16 v[18:21], v[226:229], v[198:201], v[18:21]
	v_mfma_f32_16x16x32_bf16 v[6:9], v[218:221], v[210:213], v[6:9]
	v_mfma_f32_16x16x32_bf16 v[2:5], v[226:229], v[210:213], v[2:5]
	v_mfma_f32_16x16x32_bf16 v[54:57], v[222:225], v[186:189], v[54:57]
	v_mfma_f32_16x16x32_bf16 v[50:53], v[230:233], v[186:189], v[50:53]
	v_mfma_f32_16x16x32_bf16 v[38:41], v[222:225], v[194:197], v[38:41]
	v_mfma_f32_16x16x32_bf16 v[34:37], v[230:233], v[194:197], v[34:37]
	v_mfma_f32_16x16x32_bf16 v[22:25], v[222:225], v[206:209], v[22:25]
	v_mfma_f32_16x16x32_bf16 v[18:21], v[230:233], v[206:209], v[18:21]
	v_mfma_f32_16x16x32_bf16 v[6:9], v[222:225], v[214:217], v[6:9]
	v_mfma_f32_16x16x32_bf16 v[2:5], v[230:233], v[214:217], v[2:5]
.Lgm_skip4:
	s_setprio 0
	s_add_u32 s22, s22, 0x100
	s_addc_u32 s23, s23, 0
	s_add_u32 s55, s55, 0x100
	s_addc_u32 s59, s59, 0
	s_cmp_ge_u32 s60, s41
	s_mov_b32 s24, s60
	s_barrier
	s_cbranch_scc0 .LBB0_345
	s_and_b64 vcc, exec, s[14:15]
	s_cbranch_vccz .LBB0_393
	v_mul_f32_e32 v131, 0xbfb8aa3b, v122
	v_exp_f32_e32 v131, v131
	v_mul_f32_e32 v132, 0xbfb8aa3b, v127
	v_mul_f32_e32 v133, 0xbfb8aa3b, v123
	v_exp_f32_e32 v132, v132
	v_exp_f32_e32 v133, v133
	v_add_f32_e32 v131, 1.0, v131
	v_rcp_f32_e32 v134, v131
	v_add_f32_e32 v131, 1.0, v132
	v_add_f32_e32 v132, 1.0, v133
	v_mul_f32_e32 v133, 0xbfb8aa3b, v128
	v_mul_f32_e32 v135, 0xbfb8aa3b, v124
	v_exp_f32_e32 v133, v133
	v_exp_f32_e32 v136, v135
	v_rcp_f32_e32 v135, v132
	v_mul_f32_e32 v130, 0xbfb8aa3b, v126
	v_add_f32_e32 v132, 1.0, v133
	v_add_f32_e32 v133, 1.0, v136
	v_mul_f32_e32 v136, 0xbfb8aa3b, v129
	v_exp_f32_e32 v137, v136
	v_mul_f32_e32 v136, 0xbfb8aa3b, v125
	v_exp_f32_e32 v130, v130
	v_exp_f32_e32 v156, v136
	v_rcp_f32_e32 v136, v133
	v_add_f32_e32 v133, 1.0, v137
	v_add_f32_e32 v130, 1.0, v130
	v_add_f32_e32 v137, 1.0, v156
	v_rcp_f32_e32 v130, v130
	v_rcp_f32_e32 v131, v131
	v_rcp_f32_e32 v132, v132
	v_rcp_f32_e32 v133, v133
	v_rcp_f32_e32 v137, v137
	s_cbranch_execnz .LBB0_349
